# tile-mapping division by gsz (always 4) strength-reduced to a shift at 3 GEMM tile heads (inproj, branch, resid_out)
# speedup vs baseline: 1.0048x; 1.0048x over previous
;     __device__ bool map(long L, Unit& u) const {
;     ...
;         int wgid = (int)L; { const int q = nwg / NXCD, r = nwg % NXCD, xcd = wgid % NXCD, off = wgid / NXCD; wgid = (xcd < r ? xcd * (q + 1) : r * (q + 1) + (xcd - r) * q) + off; }
;         const int nig = WGM * nN, gid = wgid / nig, fm = gid * WGM, gsz = (nM - fm) < WGM ? (nM - fm) : WGM;
;         u.pm = fm + ((wgid % nig) % gsz); u.pn = (wgid % nig) / gsz; return true;
.LBB0_200:
	s_ashr_i32 s8, s10, 3
	s_add_i32 s8, s14, s8
	s_ashr_i32 s9, s8, 31
	s_lshr_b32 s9, s9, 25
	s_add_i32 s9, s8, s9
	s_ashr_i32 s10, s9, 7
	s_lshl_b32 s10, s10, 2
	s_sub_i32 s11, 0x80, s10
	s_min_i32 s11, s11, 4
	s_and_b32 s9, s9, 0xffffff80
	s_sub_i32 s9, s8, s9
	s_ashr_i32 s8, s9, 2
	s_mul_i32 s11, s8, s11
	s_sub_i32 s9, s9, s11
	s_add_i32 s10, s10, s9

;     __device__ bool next(int i, Unit& u) const { const int t = i / 3, b = i - 3 * t; if (!so.map((long)t * so.G + so.c, u)) return false; u.pn += 8 * b; return true; }
;     __device__ bool map(long L, Unit& u) const {
;         if (L >= nwg) return false;
;         int wgid = (int)L; { const int q = nwg / NXCD, r = nwg % NXCD, xcd = wgid % NXCD, off = wgid / NXCD; wgid = (xcd < r ? xcd * (q + 1) : r * (q + 1) + (xcd - r) * q) + off; }
;         const int nig = WGM * nN, gid = wgid / nig, fm = gid * WGM, gsz = (nM - fm) < WGM ? (nM - fm) : WGM;
;         u.pm = fm + ((wgid % nig) % gsz); u.pn = (wgid % nig) / gsz; return true;
;     }
;     __device__ bool next(int i, Unit& u) const { return map((long)i * G + c, u); }
.LBB0_392:
	s_add_i32 s41, s41, 1
	s_mul_i32 s0, s41, s37
	s_mul_hi_u32 s1, s41, s18
	s_add_i32 s1, s1, s0
	s_mul_i32 s0, s41, s18
	s_add_u32 s10, s0, s19
	s_addc_u32 s11, s1, s27
	v_mov_b64_e32 v[2:3], 0xc00
	v_cmp_lt_i64_e64 s[2:3], s[10:11], v[2:3]
	v_mov_b64_e32 v[2:3], 0xbff
	v_cmp_gt_i64_e64 s[0:1], s[10:11], v[2:3]
	s_and_b64 vcc, exec, s[0:1]
	s_cbranch_vccnz .LBB0_394
	s_ashr_i32 s6, s10, 31
	s_lshr_b32 s6, s6, 29
	s_add_i32 s6, s10, s6
	s_ashr_i32 s7, s6, 3
	s_and_b32 s6, s6, -8
	s_sub_i32 s6, s10, s6
	s_cmp_lt_i32 s6, 0
	s_cselect_b32 s8, s33, 0x180
	s_mul_i32 s6, s8, s6
	s_add_i32 s6, s6, s7
	s_mul_hi_i32 s7, s6, 0x2aaaaaab
	s_lshr_b32 s8, s7, 31
	s_ashr_i32 s7, s7, 4
	s_add_i32 s7, s7, s8
	s_lshl_b32 s8, s7, 2
	s_sub_i32 s9, 0x80, s8
	s_min_i32 s9, s9, 4
	s_mulk_i32 s7, 0x60
	s_sub_i32 s7, s6, s7
	s_ashr_i32 s6, s7, 2
	s_mul_i32 s9, s6, s9
	s_sub_i32 s7, s7, s9
	s_add_i32 s8, s7, s8

;     __device__ bool map(long L, Unit& u) const {
;     ...
;         int wgid = (int)L; { const int q = nwg / NXCD, r = nwg % NXCD, xcd = wgid % NXCD, off = wgid / NXCD; wgid = (xcd < r ? xcd * (q + 1) : r * (q + 1) + (xcd - r) * q) + off; }
;         const int nig = WGM * nN, gid = wgid / nig, fm = gid * WGM, gsz = (nM - fm) < WGM ? (nM - fm) : WGM;
;         u.pm = fm + ((wgid % nig) % gsz); u.pn = (wgid % nig) / gsz; return true;
.LBB0_550:
	s_ashr_i32 s20, s22, 3
	s_add_i32 s20, s26, s20
	s_ashr_i32 s21, s20, 31
	s_lshr_b32 s21, s21, 27
	s_add_i32 s21, s20, s21
	s_ashr_i32 s22, s21, 5
	s_lshl_b32 s22, s22, 2
	s_sub_i32 s23, 0x80, s22
	s_min_i32 s23, s23, 4
	s_andn2_b32 s21, s21, 31
	s_sub_i32 s21, s20, s21
	s_ashr_i32 s20, s21, 2
	s_mul_i32 s23, s20, s23
	s_sub_i32 s21, s21, s23
	s_add_i32 s22, s22, s21
